# P2b: half of the unit epilogue's merge inputs requested at the top of the last tile into idle registers (instead of the next unit's Q rows)
# speedup vs baseline: 1.0024x; 1.0024x over previous
; #define GAS __attribute__((address_space(1)))
; __device__ __forceinline__ void attn_unit(const bool FINAL, const bool HN, LAS unsigned char* wl, const bf16_t* qb, const bf16_t* kb, const bf16_t* vb, int tq0, int dil, float sl, bf16x8 (&qr)[8], const bf16_t* nqb, const bf16_t* nkb, const bf16_t* nvb, int ntq0, int ndil, ...
;     ...
; #pragma unroll
;         for (int s = 0; s < 8; ++s) p = __builtin_amdgcn_mfma_f32_32x32x16_fp8_fp8(kf[s], q8[s], p, 0, 0, 0);
;         const float relb = (float)(32 * n + 4 * hi - 64 - r32) - 8.0f;
;     ...
;         float tmax = -1e30f;
;         if (interior && n == 2) {
; #pragma unroll
;             for (int r = 0; r < 16; ++r) { const float rel = relb + AT_CR(r); p[r] = p[r] - sl * fabsf(rel); tmax = fmaxf(tmax, p[r]); }
;         } else if (interior) {
;             const float ssl = (n < 2) ? sl : -sl;
;             if (n == 0) {
; #pragma unroll
;                 for (int r = 0; r < 16; ++r) { const float rel = relb + AT_CR(r); const float v = __builtin_fmaf(ssl, rel, p[r]); p[r] = (rel >= -64.f) ? v : -1e30f; tmax = fmaxf(tmax, p[r]); }
;             } else if (n == 4) {
; #pragma unroll
;                 for (int r = 0; r < 16; ++r) { const float rel = relb + AT_CR(r); const float v = __builtin_fmaf(ssl, rel, p[r]); p[r] = (rel <= 64.f) ? v : -1e30f; tmax = fmaxf(tmax, p[r]); }
;             } else {
; #pragma unroll
;                 for (int r = 0; r < 16; ++r) { const float rel = relb + AT_CR(r); p[r] = __builtin_fmaf(ssl, rel, p[r]); tmax = fmaxf(tmax, p[r]); }
;             }
;         } else {
; #pragma unroll
;             for (int r = 0; r < 16; ++r) { const float rel = relb + AT_CR(r); const bool ok = (rel >= lo_i) && (rel <= hi_i);
;                 p[r] = ok ? p[r] - sl * fabsf(rel) : -1e30f; tmax = fmaxf(tmax, p[r]); }
;     ...
;     if (FINAL) {
; #pragma unroll
;         for (int i = 0; i < 8; ++i) { const int row = 4 * i + rr0, c = cs ^ (row & 15); const size_t off = (size_t)(tq0 + dil * row) * 128 + 8 * c;
;             a0[i] = __builtin_nontemporal_load((const GAS v4u*)(part0 + off)); a1v[i] = __builtin_nontemporal_load((const GAS v4u*)(part1 + off)); } }
.LBB0_484:
	s_cmpk_lg_i32 s15, 0x80
	s_cbranch_scc1 mk_p2b_m_skip
	v_add_u32_e32 v68, s94, v201
	v_ashrrev_i32_e32 v69, 31, v68
	v_lshlrev_b64 v[70:71], 8, v[68:69]
	v_lshl_or_b32 v70, v164, 1, v70
	v_lshl_add_u64 v[74:75], s[56:57], 0, v[70:71]
	v_lshl_add_u64 v[76:77], s[58:59], 0, v[70:71]
	global_load_dwordx4 v[82:85], v[74:75], off nt
	global_load_dwordx4 v[86:89], v[76:77], off nt
	v_add_u32_e32 v68, 4, v201
	v_add_u32_e32 v68, s94, v68
	v_ashrrev_i32_e32 v69, 31, v68
	v_lshlrev_b64 v[70:71], 8, v[68:69]
	v_lshl_or_b32 v70, v166, 1, v70
	v_lshl_add_u64 v[74:75], s[56:57], 0, v[70:71]
	v_lshl_add_u64 v[76:77], s[58:59], 0, v[70:71]
	global_load_dwordx4 v[90:93], v[74:75], off nt
	global_load_dwordx4 v[94:97], v[76:77], off nt
	v_add_u32_e32 v68, s94, v199
	v_ashrrev_i32_e32 v69, 31, v68
	v_lshlrev_b64 v[70:71], 8, v[68:69]
	v_lshl_or_b32 v70, v168, 1, v70
	v_lshl_add_u64 v[74:75], s[56:57], 0, v[70:71]
	v_lshl_add_u64 v[76:77], s[58:59], 0, v[70:71]
	global_load_dwordx4 v[98:101], v[74:75], off nt
	global_load_dwordx4 v[102:105], v[76:77], off nt
	v_add_u32_e32 v68, s94, v203
	v_ashrrev_i32_e32 v69, 31, v68
	v_lshlrev_b64 v[70:71], 8, v[68:69]
	v_lshl_or_b32 v70, v170, 1, v70
	v_lshl_add_u64 v[74:75], s[56:57], 0, v[70:71]
	v_lshl_add_u64 v[76:77], s[58:59], 0, v[70:71]
	global_load_dwordx4 v[106:109], v[74:75], off nt
	global_load_dwordx4 v[110:113], v[76:77], off nt
mk_p2b_m_skip:
	s_waitcnt lgkmcnt(0)
	v_mfma_f32_32x32x16_fp8_fp8 v[66:81], v[66:67], v[120:121], 0
	v_add_u32_e32 v0, s4, v202
	v_cvt_f32_i32_e32 v0, v0
	s_cmp_lg_u32 s15, 64
	s_cselect_b64 s[6:7], -1, 0
	s_or_b64 s[6:7], s[74:75], s[6:7]
	v_add_f32_e32 v0, 0xc1000000, v0
	s_mov_b64 s[4:5], -1
	v_mfma_f32_32x32x16_fp8_fp8 v[66:81], v[150:151], v[122:123], v[66:81]
	s_and_b64 vcc, exec, s[6:7]
	v_mfma_f32_32x32x16_fp8_fp8 v[66:81], v[148:149], v[124:125], v[66:81]
	v_add_f32_e32 v148, 0x41000000, v0
	v_mfma_f32_32x32x16_fp8_fp8 v[66:81], v[146:147], v[126:127], v[66:81]
	v_mfma_f32_32x32x16_fp8_fp8 v[66:81], v[144:145], v[128:129], v[66:81]
	v_mfma_f32_32x32x16_fp8_fp8 v[66:81], v[138:139], v[130:131], v[66:81]
	v_mfma_f32_32x32x16_fp8_fp8 v[66:81], v[140:141], v[132:133], v[66:81]
	v_mfma_f32_32x32x16_fp8_fp8 v[66:81], v[142:143], v[134:135], v[66:81]
	s_cbranch_vccz .LBB0_495
	s_andn2_b64 vcc, exec, s[74:75]
	s_cbranch_vccnz .LBB0_487
	v_add_f32_e32 v139, 0x41100000, v0
	v_cmp_ge_f32_e32 vcc, v139, v117
	v_cmp_le_f32_e64 s[6:7], v139, v119
	v_and_b32_e32 v138, 0x7fffffff, v148
	v_and_b32_e32 v139, 0x7fffffff, v139
	v_cmp_ge_f32_e64 s[4:5], v148, v118
	v_cmp_le_f32_e64 s[8:9], v148, v116
	s_nop 1
	v_pk_fma_f32 v[138:139], v[114:115], v[138:139], v[66:67] neg_lo:[1,0,0] neg_hi:[1,0,0]
	s_and_b64 vcc, vcc, s[6:7]
	v_cndmask_b32_e32 v139, v245, v139, vcc
	s_and_b64 vcc, s[4:5], s[8:9]
	v_pk_add_f32 v[140:141], v[0:1], s[12:13] op_sel_hi:[0,1]
	v_cndmask_b32_e32 v138, v245, v138, vcc
	v_cmp_ge_f32_e32 vcc, v141, v117
	v_cmp_ge_f32_e64 s[4:5], v140, v118
	v_cmp_le_f32_e64 s[6:7], v141, v119
	v_cmp_le_f32_e64 s[8:9], v140, v116
	v_and_b32_e32 v141, 0x7fffffff, v141
	v_and_b32_e32 v140, 0x7fffffff, v140
	v_pk_fma_f32 v[140:141], v[114:115], v[140:141], v[68:69] neg_lo:[1,0,0] neg_hi:[1,0,0]
	s_and_b64 vcc, vcc, s[6:7]
	v_cndmask_b32_e32 v141, v245, v141, vcc
	s_and_b64 vcc, s[4:5], s[8:9]
	v_max3_f32 v142, v138, s92, v139
	v_cndmask_b32_e32 v140, v245, v140, vcc
	v_max3_f32 v144, v142, v140, v141
	v_pk_add_f32 v[142:143], v[0:1], s[16:17] op_sel_hi:[0,1]
	v_cmp_ge_f32_e32 vcc, v143, v117
	v_cmp_ge_f32_e64 s[4:5], v142, v118
	v_cmp_le_f32_e64 s[6:7], v143, v119
	v_cmp_le_f32_e64 s[8:9], v142, v116
	v_and_b32_e32 v143, 0x7fffffff, v143
	v_and_b32_e32 v142, 0x7fffffff, v142
	v_pk_fma_f32 v[142:143], v[114:115], v[142:143], v[70:71] neg_lo:[1,0,0] neg_hi:[1,0,0]
	s_and_b64 vcc, vcc, s[6:7]
	v_cndmask_b32_e32 v143, v245, v143, vcc
	s_and_b64 vcc, s[4:5], s[8:9]
	v_cndmask_b32_e32 v142, v245, v142, vcc
	v_max3_f32 v146, v144, v142, v143
	v_pk_add_f32 v[144:145], v[0:1], s[18:19] op_sel_hi:[0,1]
	v_cmp_ge_f32_e32 vcc, v145, v117
	v_cmp_ge_f32_e64 s[4:5], v144, v118
	v_cmp_le_f32_e64 s[6:7], v145, v119
	v_cmp_le_f32_e64 s[8:9], v144, v116
	v_and_b32_e32 v145, 0x7fffffff, v145
	v_and_b32_e32 v144, 0x7fffffff, v144
	v_pk_fma_f32 v[144:145], v[114:115], v[144:145], v[72:73] neg_lo:[1,0,0] neg_hi:[1,0,0]
	s_and_b64 vcc, vcc, s[6:7]
	v_cndmask_b32_e32 v145, v245, v145, vcc
	s_and_b64 vcc, s[4:5], s[8:9]
	v_cndmask_b32_e32 v144, v245, v144, vcc
	v_max3_f32 v149, v146, v144, v145
	v_pk_add_f32 v[146:147], v[0:1], s[20:21] op_sel_hi:[0,1]
	v_cmp_ge_f32_e32 vcc, v147, v117
	v_cmp_ge_f32_e64 s[4:5], v146, v118
	v_cmp_le_f32_e64 s[6:7], v147, v119
	v_cmp_le_f32_e64 s[8:9], v146, v116
	v_and_b32_e32 v147, 0x7fffffff, v147
	v_and_b32_e32 v146, 0x7fffffff, v146
	v_pk_fma_f32 v[146:147], v[114:115], v[146:147], v[74:75] neg_lo:[1,0,0] neg_hi:[1,0,0]
	s_and_b64 vcc, vcc, s[6:7]
	v_cndmask_b32_e32 v147, v245, v147, vcc
	s_and_b64 vcc, s[4:5], s[8:9]
	v_pk_add_f32 v[150:151], v[0:1], s[22:23] op_sel_hi:[0,1]
	v_cndmask_b32_e32 v146, v245, v146, vcc
	v_cmp_ge_f32_e32 vcc, v151, v117
	v_cmp_ge_f32_e64 s[4:5], v150, v118
	v_cmp_le_f32_e64 s[6:7], v151, v119
	v_cmp_le_f32_e64 s[8:9], v150, v116
	v_and_b32_e32 v151, 0x7fffffff, v151
	v_and_b32_e32 v150, 0x7fffffff, v150
	v_pk_fma_f32 v[150:151], v[114:115], v[150:151], v[76:77] neg_lo:[1,0,0] neg_hi:[1,0,0]
	s_and_b64 vcc, vcc, s[6:7]
	v_cndmask_b32_e32 v151, v245, v151, vcc
	s_and_b64 vcc, s[4:5], s[8:9]
	v_pk_add_f32 v[152:153], v[0:1], s[24:25] op_sel_hi:[0,1]
	v_cndmask_b32_e32 v150, v245, v150, vcc
	v_cmp_ge_f32_e32 vcc, v153, v117
	v_cmp_ge_f32_e64 s[4:5], v152, v118
	v_cmp_le_f32_e64 s[6:7], v153, v119
	v_cmp_le_f32_e64 s[8:9], v152, v116
	v_and_b32_e32 v153, 0x7fffffff, v153
	v_and_b32_e32 v152, 0x7fffffff, v152
	v_pk_fma_f32 v[152:153], v[114:115], v[152:153], v[78:79] neg_lo:[1,0,0] neg_hi:[1,0,0]
	s_and_b64 vcc, vcc, s[6:7]
	v_cndmask_b32_e32 v153, v245, v153, vcc
	s_and_b64 vcc, s[4:5], s[8:9]
	v_pk_add_f32 v[154:155], v[0:1], s[26:27] op_sel_hi:[0,1]
	v_cndmask_b32_e32 v152, v245, v152, vcc
	v_cmp_ge_f32_e32 vcc, v155, v117
	v_cmp_ge_f32_e64 s[4:5], v154, v118
	v_cmp_le_f32_e64 s[6:7], v155, v119
	v_cmp_le_f32_e64 s[8:9], v154, v116
	v_and_b32_e32 v155, 0x7fffffff, v155
	v_and_b32_e32 v154, 0x7fffffff, v154
	v_max3_f32 v149, v149, v146, v147
	v_pk_fma_f32 v[154:155], v[114:115], v[154:155], v[80:81] neg_lo:[1,0,0] neg_hi:[1,0,0]
	s_and_b64 vcc, vcc, s[6:7]
	v_max3_f32 v149, v149, v150, v151
	v_cndmask_b32_e32 v155, v245, v155, vcc
	s_and_b64 vcc, s[4:5], s[8:9]
	v_max3_f32 v149, v149, v152, v153
	v_cndmask_b32_e32 v154, v245, v154, vcc
	v_max3_f32 v161, v149, v154, v155
	s_mov_b64 s[4:5], 0

; #define AT_PK8(P, BASE, OUT) do { const unsigned a4 = pg8::pk_fp8x4((f32x4){P[BASE + 0], P[BASE + 1], P[BASE + 2], P[BASE + 3]}), b4 = pg8::pk_fp8x4((f32x4){P[BASE + 4], P[BASE + 5], P[BASE + 6], P[BASE + 7]}); \
;         auto r0 = __builtin_amdgcn_permlane32_swap(a4, b4, false, false); OUT = (long)(((unsigned long long)r0[1] << 32) | (unsigned long long)r0[0]); } while (0)
; __device__ __forceinline__ void attn_unit(const bool FINAL, const bool HN, LAS unsigned char* wl, const bf16_t* qb, const bf16_t* kb, const bf16_t* vb, int tq0, int dil, float sl, bf16x8 (&qr)[8], const bf16_t* nqb, const bf16_t* nkb, const bf16_t* nvb, int ntq0, int ndil, ...
;     ...
;         float ps = 0.f;
; #pragma unroll
;         for (int r = 0; r < 16; ++r) { p[r] = __builtin_amdgcn_exp2f(p[r] - mn); ps += p[r]; }
;         { auto rr = __builtin_amdgcn_permlane32_swap(__float_as_uint(ps), __float_as_uint(ps), false, false); ps = __uint_as_float(rr[0]) + __uint_as_float(rr[1]); }
;         l_run = l_run * alpha + ps;
;         long pa0, pa1;
;     ...
;         AT_PK8(p, 0, pa0); AT_PK8(p, 8, pa1);
;     ...
;         if (n < 4 || HN) asm volatile("s_waitcnt vmcnt(4)" ::: "memory");
;         else asm volatile("s_waitcnt vmcnt(0)" ::: "memory");
.LBB0_501:
	v_pk_add_f32 v[138:139], v[138:139], v[160:161] op_sel:[0,1] op_sel_hi:[1,1] neg_lo:[0,1] neg_hi:[0,1]
	v_pk_add_f32 v[140:141], v[140:141], v[160:161] op_sel:[0,1] op_sel_hi:[1,1] neg_lo:[0,1] neg_hi:[0,1]
	v_exp_f32_e32 v138, v138
	v_pk_add_f32 v[142:143], v[142:143], v[160:161] op_sel:[0,1] op_sel_hi:[1,1] neg_lo:[0,1] neg_hi:[0,1]
	v_exp_f32_e32 v139, v139
	v_pk_add_f32 v[144:145], v[144:145], v[160:161] op_sel:[0,1] op_sel_hi:[1,1] neg_lo:[0,1] neg_hi:[0,1]
	v_exp_f32_e32 v140, v140
	v_pk_add_f32 v[146:147], v[146:147], v[160:161] op_sel:[0,1] op_sel_hi:[1,1] neg_lo:[0,1] neg_hi:[0,1]
	v_exp_f32_e32 v141, v141
	v_pk_add_f32 v[150:151], v[150:151], v[160:161] op_sel:[0,1] op_sel_hi:[1,1] neg_lo:[0,1] neg_hi:[0,1]
	v_exp_f32_e32 v142, v142
	v_pk_add_f32 v[152:153], v[152:153], v[160:161] op_sel:[0,1] op_sel_hi:[1,1] neg_lo:[0,1] neg_hi:[0,1]
	v_exp_f32_e32 v143, v143
	v_pk_add_f32 v[154:155], v[154:155], v[160:161] op_sel:[0,1] op_sel_hi:[1,1] neg_lo:[0,1] neg_hi:[0,1]
	v_exp_f32_e32 v144, v144
	v_cvt_pk_fp8_f32 v66, v138, v139
	v_exp_f32_e32 v145, v145
	v_cvt_pk_fp8_f32 v66, v140, v141 op_sel:[0,0,1]
	v_exp_f32_e32 v146, v146
	v_pk_add_f32 v[70:71], v[138:139], v[140:141]
	v_exp_f32_e32 v147, v147
	v_cvt_pk_fp8_f32 v67, v142, v143
	v_exp_f32_e32 v150, v150
	v_cvt_pk_fp8_f32 v67, v144, v145 op_sel:[0,0,1]
	v_exp_f32_e32 v151, v151
	v_pk_add_f32 v[72:73], v[142:143], v[144:145]
	v_exp_f32_e32 v152, v152
	v_cvt_pk_fp8_f32 v68, v146, v147
	v_exp_f32_e32 v153, v153
	v_pk_add_f32 v[70:71], v[70:71], v[72:73]
	v_exp_f32_e32 v154, v154
	v_cvt_pk_fp8_f32 v68, v150, v151 op_sel:[0,0,1]
	v_exp_f32_e32 v155, v155
	v_pk_add_f32 v[74:75], v[146:147], v[150:151]
	v_cvt_pk_fp8_f32 v69, v152, v153
	s_nop 0
	v_cvt_pk_fp8_f32 v69, v154, v155 op_sel:[0,0,1]
	v_pk_add_f32 v[76:77], v[152:153], v[154:155]
	v_pk_add_f32 v[74:75], v[74:75], v[76:77]
	v_pk_add_f32 v[70:71], v[70:71], v[74:75]
	v_add_f32_e32 v142, v70, v71
	v_mov_b32_e32 v143, v142
	s_nop 1
	v_permlane32_swap_b32_e32 v142, v143
	v_permlane32_swap_b32_e32 v66, v67
	v_permlane32_swap_b32_e32 v68, v69
	s_mov_b64 s[4:5], -1
	s_and_b64 vcc, exec, s[78:79]
	s_cbranch_vccz .LBB0_503
	s_waitcnt vmcnt(8)
	s_mov_b64 s[4:5], 0

; #define GAS __attribute__((address_space(1)))
; #define LAS __attribute__((address_space(3)))
; __device__ __forceinline__ unsigned cvtpk(float lo, float hi) { unsigned r; asm volatile("v_cvt_pk_bf16_f32 %0, %1, %2" : "=v"(r) : "v"(lo), "v"(hi)); return r; }
; __device__ __forceinline__ void attn_unit(const bool FINAL, const bool HN, LAS unsigned char* wl, const bf16_t* qb, const bf16_t* kb, const bf16_t* vb, int tq0, int dil, float sl, bf16x8 (&qr)[8], const bf16_t* nqb, const bf16_t* nkb, const bf16_t* nvb, int ntq0, int ndil, ...
;     ...
;     if (HN) at_load_q(qr, nqb, ntq0, ndil, lane);
;     const int tq = tq0 + dil * r32;
;     v4u a0[8], a1v[8];
;     if (FINAL) {
; #pragma unroll
;         for (int i = 0; i < 8; ++i) { const int row = 4 * i + rr0, c = cs ^ (row & 15); const size_t off = (size_t)(tq0 + dil * row) * 128 + 8 * c;
;             a0[i] = __builtin_nontemporal_load((const GAS v4u*)(part0 + off)); a1v[i] = __builtin_nontemporal_load((const GAS v4u*)(part1 + off)); } }
;     float osc, c1 = 0.f, c2 = 0.f;
;     if (!FINAL) { osc = 1.0f / l_run; if (hi == 0) *(GAS f32x2*)(ml + (size_t)tq * 2) = (f32x2){m_run, l_run}; }
;     else {
;         const f32x2 s1 = st1, s2 = st2;
;         const float M = fmaxf(fmaxf(s1.x, s2.x), m_run);
;         const float a1 = __builtin_amdgcn_exp2f(s1.x - M) * s1.y, a2 = __builtin_amdgcn_exp2f(s2.x - M) * s2.y, a3 = __builtin_amdgcn_exp2f(m_run - M);
;         const float inv = 1.0f / (a1 + a2 + a3 * l_run);
;         c1 = a1 * inv; c2 = a2 * inv; osc = a3 * inv;
;     }
;     {
;         LAS unsigned char* wrow = vbuf + r32 * 256 + hi * 8; const int qx = r32 & 15;
; #pragma unroll
;         for (int d0 = 0; d0 < 4; ++d0)
; #pragma unroll
;             for (int g4 = 0; g4 < 4; ++g4) { u32x2 w; w.x = cvtpk(oT[d0][4 * g4] * osc, oT[d0][4 * g4 + 1] * osc); w.y = cvtpk(oT[d0][4 * g4 + 2] * osc, oT[d0][4 * g4 + 3] * osc);
;                 *(LAS u32x2*)(wrow + (((4 * d0 + g4) ^ qx) << 4)) = w; }
.LBB0_513:
	s_waitcnt vmcnt(0)
	v_mov_b32_e32 v204, v82
	v_mov_b32_e32 v205, v83
	v_mov_b32_e32 v206, v84
	v_mov_b32_e32 v207, v85
	v_mov_b32_e32 v154, v86
	v_mov_b32_e32 v155, v87
	v_mov_b32_e32 v156, v88
	v_mov_b32_e32 v157, v89
	v_mov_b32_e32 v150, v90
	v_mov_b32_e32 v151, v91
	v_mov_b32_e32 v152, v92
	v_mov_b32_e32 v153, v93
	v_mov_b32_e32 v146, v94
	v_mov_b32_e32 v147, v95
	v_mov_b32_e32 v148, v96
	v_mov_b32_e32 v149, v97
	v_mov_b32_e32 v142, v98
	v_mov_b32_e32 v143, v99
	v_mov_b32_e32 v144, v100
	v_mov_b32_e32 v145, v101
	v_mov_b32_e32 v138, v102
	v_mov_b32_e32 v139, v103
	v_mov_b32_e32 v140, v104
	v_mov_b32_e32 v141, v105
	v_mov_b32_e32 v134, v106
	v_mov_b32_e32 v135, v107
	v_mov_b32_e32 v136, v108
	v_mov_b32_e32 v137, v109
	v_mov_b32_e32 v130, v110
	v_mov_b32_e32 v131, v111
	v_mov_b32_e32 v132, v112
	v_mov_b32_e32 v133, v113
	s_and_b64 vcc, exec, s[46:47]
	s_cbranch_vccz .LBB0_515
	v_or_b32_e32 v0, s14, v200
	v_lshlrev_b32_e32 v0, 8, v0
	v_lshl_add_u64 v[66:67], s[10:11], 0, v[0:1]
	v_lshl_add_u64 v[66:67], v[162:163], 1, v[66:67]
	global_load_dwordx4 v[82:85], v[66:67], off
	global_load_dwordx4 v[86:89], v[66:67], off offset:32
	global_load_dwordx4 v[90:93], v[66:67], off offset:64
	global_load_dwordx4 v[94:97], v[66:67], off offset:96
	global_load_dwordx4 v[98:101], v[66:67], off offset:128
	global_load_dwordx4 v[102:105], v[66:67], off offset:160
	global_load_dwordx4 v[106:109], v[66:67], off offset:192
	global_load_dwordx4 v[110:113], v[66:67], off offset:224
.LBB0_515:
	v_add_u32_e32 v196, s94, v201
	v_ashrrev_i32_e32 v197, 31, v196
	v_lshlrev_b64 v[66:67], 8, v[196:197]
	v_lshlrev_b32_e32 v0, 1, v164
	v_or_b32_e32 v66, v66, v0
	v_lshl_add_u64 v[68:69], s[58:59], 0, v[66:67]
	v_lshl_add_u64 v[66:67], s[56:57], 0, v[66:67]
	v_add_u32_e32 v66, 4, v201
	v_add_u32_e32 v194, s94, v66
	v_ashrrev_i32_e32 v195, 31, v194
	v_lshlrev_b64 v[66:67], 8, v[194:195]
	v_lshl_or_b32 v66, v166, 1, v66
	v_add_u32_e32 v192, s94, v199
	v_lshl_add_u64 v[68:69], s[58:59], 0, v[66:67]
	v_lshl_add_u64 v[66:67], s[56:57], 0, v[66:67]
	v_ashrrev_i32_e32 v193, 31, v192
	v_lshlrev_b64 v[66:67], 8, v[192:193]
	v_lshl_or_b32 v66, v168, 1, v66
	v_add_u32_e32 v190, s94, v203
	v_lshl_add_u64 v[68:69], s[58:59], 0, v[66:67]
	v_lshl_add_u64 v[66:67], s[56:57], 0, v[66:67]
	v_ashrrev_i32_e32 v191, 31, v190
	v_lshlrev_b64 v[66:67], 8, v[190:191]
	v_lshl_or_b32 v66, v170, 1, v66
	v_lshl_add_u64 v[68:69], s[58:59], 0, v[66:67]
	v_lshl_add_u64 v[66:67], s[56:57], 0, v[66:67]
	v_add_u32_e32 v66, 16, v201
	v_add_u32_e32 v188, s94, v66
	v_ashrrev_i32_e32 v189, 31, v188
	v_lshlrev_b64 v[66:67], 8, v[188:189]
	v_or_b32_e32 v66, v66, v0
	v_add_u32_e32 v0, 20, v201
	v_add_u32_e32 v186, s94, v0
	v_lshl_add_u64 v[68:69], s[58:59], 0, v[66:67]
	v_lshl_add_u64 v[66:67], s[56:57], 0, v[66:67]
	v_ashrrev_i32_e32 v187, 31, v186
	global_load_dwordx4 v[126:129], v[66:67], off nt
	v_lshlrev_b64 v[66:67], 8, v[186:187]
	v_lshl_or_b32 v66, v172, 1, v66
	v_add_u32_e32 v184, s94, v208
	global_load_dwordx4 v[122:125], v[68:69], off nt
	v_lshl_add_u64 v[68:69], s[58:59], 0, v[66:67]
	v_lshl_add_u64 v[66:67], s[56:57], 0, v[66:67]
	v_ashrrev_i32_e32 v185, 31, v184
	global_load_dwordx4 v[118:121], v[66:67], off nt
	v_lshlrev_b64 v[66:67], 8, v[184:185]
	v_lshl_or_b32 v66, v174, 1, v66
	global_load_dwordx4 v[114:117], v[68:69], off nt
	v_lshl_add_u64 v[68:69], s[58:59], 0, v[66:67]
	s_waitcnt vmcnt(0)
	v_max3_f32 v0, v180, v178, v161
	global_load_dwordx4 v[74:77], v[68:69], off nt
	v_sub_f32_e32 v68, v180, v0
	v_exp_f32_e32 v158, v68
	v_sub_f32_e32 v68, v178, v0
	v_sub_f32_e32 v0, v161, v0
	v_exp_f32_e32 v159, v0
	v_exp_f32_e32 v0, v68
	v_add_u32_e32 v182, s94, v209
	v_ashrrev_i32_e32 v183, 31, v182
	v_mov_b32_e32 v70, v181
	v_lshlrev_b64 v[72:73], 8, v[182:183]
	v_pk_mul_f32 v[160:161], v[70:71], v[158:159]
	v_lshl_add_u64 v[66:67], s[56:57], 0, v[66:67]
	v_lshl_or_b32 v72, v176, 1, v72
	v_fma_f32 v70, v179, v0, v160
	global_load_dwordx4 v[78:81], v[66:67], off nt
	v_lshl_add_u64 v[66:67], s[58:59], 0, v[72:73]
	v_add_f32_e32 v158, v70, v161
	v_lshl_add_u64 v[70:71], s[56:57], 0, v[72:73]
	global_load_dwordx4 v[66:69], v[66:67], off nt
	v_div_scale_f32 v161, s[4:5], v158, v158, 1.0
	global_load_dwordx4 v[70:73], v[70:71], off nt
	v_rcp_f32_e32 v178, v161
	v_mul_f32_e32 v179, v179, v0
	v_fma_f32 v0, -v161, v178, 1.0
	v_fmac_f32_e32 v178, v0, v178
	v_div_scale_f32 v0, vcc, 1.0, v158, 1.0
	v_mul_f32_e32 v180, v0, v178
	v_fma_f32 v181, -v161, v180, v0
	v_fmac_f32_e32 v180, v181, v178
	v_fma_f32 v0, -v161, v180, v0
	v_div_fmas_f32 v0, v0, v178, v180
	v_div_fixup_f32 v158, v0, v158, 1.0
	v_mul_f32_e32 v0, v160, v158
	v_mul_f32_e32 v178, v179, v158
	v_mul_f32_e32 v158, v159, v158
	v_mul_f32_e32 v50, v158, v50
	v_mul_f32_e32 v51, v158, v51
	v_cvt_pk_bf16_f32 v50, v50, v51
	v_mul_f32_e32 v51, v158, v52
	v_mul_f32_e32 v52, v158, v53
	v_cvt_pk_bf16_f32 v51, v51, v52
	v_add_u32_e32 v52, v210, v211
	ds_write_b64 v52, v[50:51] offset:8192
	v_mul_f32_e32 v50, v158, v54
	v_mul_f32_e32 v51, v158, v55
	v_cvt_pk_bf16_f32 v50, v50, v51
	v_mul_f32_e32 v51, v158, v56
	v_mul_f32_e32 v52, v158, v57
	v_cvt_pk_bf16_f32 v51, v51, v52
	ds_write_b64 v221, v[50:51] offset:8192
	v_mul_f32_e32 v50, v158, v58
	v_mul_f32_e32 v51, v158, v59
	v_cvt_pk_bf16_f32 v50, v50, v51
	v_mul_f32_e32 v51, v158, v60
	v_mul_f32_e32 v52, v158, v61
	v_cvt_pk_bf16_f32 v51, v51, v52
	ds_write_b64 v222, v[50:51] offset:8192
	v_mul_f32_e32 v50, v158, v62
	v_mul_f32_e32 v51, v158, v63
	v_cvt_pk_bf16_f32 v50, v50, v51
	v_mul_f32_e32 v51, v158, v64
	v_mul_f32_e32 v34, v158, v34
	v_mul_f32_e32 v35, v158, v35
	v_mul_f32_e32 v52, v158, v65
; __device__ __forceinline__ unsigned pk_fp8x4(const f32x4 v) { int r = __builtin_amdgcn_cvt_pk_fp8_f32(v[0], v[1], 0, false); r = __builtin_amdgcn_cvt_pk_fp8_f32(v[2], v[3], r, true); return (unsigned)r; }
; #define GAS __attribute__((address_space(1)))
; #define LAS __attribute__((address_space(3)))
; __device__ __forceinline__ unsigned cvtpk(float lo, float hi) { unsigned r; asm volatile("v_cvt_pk_bf16_f32 %0, %1, %2" : "=v"(r) : "v"(lo), "v"(hi)); return r; }
; #define SBAR() __builtin_amdgcn_sched_barrier(0)
; #define AT_MIX(F, J) do { f8[2 * J] = w1 * bf2f(a0[i].F & 0xffffu) + w2 * bf2f(a1v[i].F & 0xffffu) + bf2f(o.F & 0xffffu); \
;                 f8[2 * J + 1] = w1 * bf2f(a0[i].F >> 16) + w2 * bf2f(a1v[i].F >> 16) + bf2f(o.F >> 16); } while (0)
; __device__ __forceinline__ void attn_unit(const bool FINAL, const bool HN, LAS unsigned char* wl, const bf16_t* qb, const bf16_t* kb, const bf16_t* vb, int tq0, int dil, float sl, bf16x8 (&qr)[8], const bf16_t* nqb, const bf16_t* nkb, const bf16_t* nvb, int ntq0, int ndil, ...
;     ...
;             for (int g4 = 0; g4 < 4; ++g4) { u32x2 w; w.x = cvtpk(oT[d0][4 * g4] * osc, oT[d0][4 * g4 + 1] * osc); w.y = cvtpk(oT[d0][4 * g4 + 2] * osc, oT[d0][4 * g4 + 3] * osc);
;                 *(LAS u32x2*)(wrow + (((4 * d0 + g4) ^ qx) << 4)) = w; }
;     }
;     asm volatile("s_waitcnt lgkmcnt(0)" ::: "memory"); SBAR();
;     if (!FINAL) {
; #pragma unroll
;         for (int i = 0; i < 8; ++i) a0[i] = *(const LAS v4u*)(vbuf + (4 * i + rr0) * 256 + cs * 16);
; #pragma unroll
;         for (int i = 0; i < 8; ++i) { const int row = 4 * i + rr0, c = cs ^ (row & 15);
;             *(GAS v4u*)(part + (size_t)(tq0 + dil * row) * 128 + 8 * c) = a0[i]; }
;     } else {
; #pragma unroll
;         for (int i = 0; i < 8; ++i) { const int row = 4 * i + rr0, c = cs ^ (row & 15);
;             const float w1 = __shfl(c1, row), w2 = __shfl(c2, row);
;             const v4u o = *(const LAS v4u*)(vbuf + row * 256 + cs * 16);
;             float f8[8];
;     ...
;             AT_MIX(x, 0); AT_MIX(y, 1); AT_MIX(z, 2); AT_MIX(w, 3);
;     ...
;             u32x2 r8; r8.x = pg8::pk_fp8x4((f32x4){f8[0], f8[1], f8[2], f8[3]}); r8.y = pg8::pk_fp8x4((f32x4){f8[4], f8[5], f8[6], f8[7]});
;             *(GAS u32x2*)((GAS unsigned char*)yout + (size_t)(tq0 + dil * row) * 3072 + 8 * c) = r8; }
	v_cvt_pk_bf16_f32 v51, v51, v52
	ds_write_b64 v223, v[50:51] offset:8192
	v_cvt_pk_bf16_f32 v34, v34, v35
	v_mul_f32_e32 v35, v158, v36
	v_mul_f32_e32 v36, v158, v37
	v_cvt_pk_bf16_f32 v35, v35, v36
	ds_write_b64 v224, v[34:35] offset:8192
	v_mul_f32_e32 v34, v158, v38
	v_mul_f32_e32 v35, v158, v39
	v_cvt_pk_bf16_f32 v34, v34, v35
	v_mul_f32_e32 v35, v158, v40
	v_mul_f32_e32 v36, v158, v41
	v_cvt_pk_bf16_f32 v35, v35, v36
	ds_write_b64 v225, v[34:35] offset:8192
	v_mul_f32_e32 v34, v158, v42
	v_mul_f32_e32 v35, v158, v43
	v_cvt_pk_bf16_f32 v34, v34, v35
	v_mul_f32_e32 v35, v158, v44
	v_mul_f32_e32 v36, v158, v45
	v_cvt_pk_bf16_f32 v35, v35, v36
	ds_write_b64 v226, v[34:35] offset:8192
	v_mul_f32_e32 v34, v158, v46
	v_mul_f32_e32 v35, v158, v47
	v_cvt_pk_bf16_f32 v34, v34, v35
	v_mul_f32_e32 v35, v158, v48
	v_mul_f32_e32 v18, v158, v18
	v_mul_f32_e32 v19, v158, v19
	v_mul_f32_e32 v36, v158, v49
	v_cvt_pk_bf16_f32 v35, v35, v36
	ds_write_b64 v227, v[34:35] offset:8192
	v_cvt_pk_bf16_f32 v18, v18, v19
	v_mul_f32_e32 v19, v158, v20
	v_mul_f32_e32 v20, v158, v21
	v_cvt_pk_bf16_f32 v19, v19, v20
	ds_write_b64 v228, v[18:19] offset:8192
	v_mul_f32_e32 v18, v158, v22
	v_mul_f32_e32 v19, v158, v23
	v_cvt_pk_bf16_f32 v18, v18, v19
	v_mul_f32_e32 v19, v158, v24
	v_mul_f32_e32 v20, v158, v25
	v_cvt_pk_bf16_f32 v19, v19, v20
	ds_write_b64 v229, v[18:19] offset:8192
	v_mul_f32_e32 v18, v158, v26
	v_mul_f32_e32 v19, v158, v27
	v_cvt_pk_bf16_f32 v18, v18, v19
	v_mul_f32_e32 v19, v158, v28
	v_mul_f32_e32 v20, v158, v29
	v_cvt_pk_bf16_f32 v19, v19, v20
	ds_write_b64 v230, v[18:19] offset:8192
	v_mul_f32_e32 v18, v158, v30
	v_mul_f32_e32 v19, v158, v31
	v_cvt_pk_bf16_f32 v18, v18, v19
	v_mul_f32_e32 v19, v158, v32
	v_mul_f32_e32 v2, v158, v2
	v_mul_f32_e32 v3, v158, v3
	v_mul_f32_e32 v20, v158, v33
	v_cvt_pk_bf16_f32 v19, v19, v20
	ds_write_b64 v231, v[18:19] offset:8192
	v_cvt_pk_bf16_f32 v2, v2, v3
	v_mul_f32_e32 v3, v158, v4
	v_mul_f32_e32 v4, v158, v5
	v_cvt_pk_bf16_f32 v3, v3, v4
	ds_write_b64 v232, v[2:3] offset:8192
	v_mul_f32_e32 v2, v158, v6
	v_mul_f32_e32 v3, v158, v7
	v_cvt_pk_bf16_f32 v2, v2, v3
	v_mul_f32_e32 v3, v158, v8
	v_mul_f32_e32 v4, v158, v9
	v_cvt_pk_bf16_f32 v3, v3, v4
	ds_write_b64 v233, v[2:3] offset:8192
	v_mul_f32_e32 v2, v158, v10
	v_mul_f32_e32 v3, v158, v11
	v_cvt_pk_bf16_f32 v2, v2, v3
	v_mul_f32_e32 v3, v158, v12
	v_mul_f32_e32 v4, v158, v13
	v_cvt_pk_bf16_f32 v3, v3, v4
	ds_write_b64 v234, v[2:3] offset:8192
	v_mul_f32_e32 v2, v158, v14
	v_mul_f32_e32 v3, v158, v15
	v_cvt_pk_bf16_f32 v2, v2, v3
	v_mul_f32_e32 v3, v158, v16
	v_mul_f32_e32 v4, v158, v17
	v_cvt_pk_bf16_f32 v3, v3, v4
	ds_write_b64 v235, v[2:3] offset:8192
	s_waitcnt lgkmcnt(0)
	ds_read_b128 v[2:5], v236 offset:8192
	ds_read_b128 v[6:9], v237 offset:8192
	ds_bpermute_b32 v10, v246, v0
	ds_bpermute_b32 v11, v246, v178
	s_waitcnt lgkmcnt(0)
	v_lshlrev_b32_e32 v12, 16, v2
	v_and_b32_e32 v13, 0xffff0000, v2
	v_lshlrev_b32_e32 v14, 16, v3
	v_and_b32_e32 v15, 0xffff0000, v3
	v_lshlrev_b32_e32 v3, 16, v204
	v_lshlrev_b32_e32 v2, 16, v154
	v_pk_mul_f32 v[2:3], v[2:3], v[10:11]
	v_lshlrev_b32_e32 v16, 16, v4
	v_add_f32_e32 v2, v2, v3
	v_add_f32_e32 v12, v2, v12
	v_and_b32_e32 v3, 0xffff0000, v204
	v_and_b32_e32 v2, 0xffff0000, v154
	v_pk_mul_f32 v[2:3], v[2:3], v[10:11]
	v_and_b32_e32 v4, 0xffff0000, v4
	v_add_f32_e32 v2, v2, v3
	v_add_f32_e32 v13, v2, v13
	v_lshlrev_b32_e32 v3, 16, v205
	v_lshlrev_b32_e32 v2, 16, v155
	v_pk_mul_f32 v[2:3], v[2:3], v[10:11]
	s_nop 0
	v_add_f32_e32 v2, v2, v3
	v_add_f32_e32 v14, v2, v14
	v_and_b32_e32 v3, 0xffff0000, v205
	v_and_b32_e32 v2, 0xffff0000, v155
	v_pk_mul_f32 v[2:3], v[2:3], v[10:11]
	s_nop 0
	v_add_f32_e32 v2, v2, v3
	v_add_f32_e32 v15, v2, v15
	v_lshlrev_b32_e32 v3, 16, v206
	v_lshlrev_b32_e32 v2, 16, v156
	v_pk_mul_f32 v[2:3], v[2:3], v[10:11]
	s_nop 0
	v_add_f32_e32 v2, v2, v3
	v_add_f32_e32 v16, v2, v16
	v_and_b32_e32 v3, 0xffff0000, v206
	v_and_b32_e32 v2, 0xffff0000, v156
	v_pk_mul_f32 v[2:3], v[2:3], v[10:11]
	s_nop 0
	v_add_f32_e32 v2, v2, v3
	v_add_f32_e32 v4, v2, v4
	v_lshlrev_b32_e32 v3, 16, v207
	v_lshlrev_b32_e32 v2, 16, v157
	v_pk_mul_f32 v[2:3], v[2:3], v[10:11]
	s_nop 0
	v_add_f32_e32 v2, v2, v3
	v_lshlrev_b32_e32 v3, 16, v5
	v_add_f32_e32 v17, v2, v3
	v_and_b32_e32 v3, 0xffff0000, v207
	v_and_b32_e32 v2, 0xffff0000, v157
	v_pk_mul_f32 v[2:3], v[2:3], v[10:11]
	v_mov_b32_e32 v10, 0
	v_mov_b32_e32 v11, 0
	v_cvt_pk_fp8_f32 v10, v12, v13
	v_cvt_pk_fp8_f32 v11, v16, v4
	v_add_f32_e32 v2, v2, v3
	v_and_b32_e32 v3, 0xffff0000, v5
	v_add_f32_e32 v2, v2, v3
	v_cvt_pk_fp8_f32 v10, v14, v15 op_sel:[0,0,1]
	v_cvt_pk_fp8_f32 v11, v17, v2 op_sel:[0,0,1]
	v_mov_b64_e32 v[2:3], s[54:55]
	v_mad_i64_i32 v[4:5], s[4:5], v196, s97, v[2:3]
	v_lshl_add_u64 v[4:5], v[4:5], 0, v[164:165]
	global_store_dwordx2 v[4:5], v[10:11], off
	ds_bpermute_b32 v4, v247, v0
	ds_bpermute_b32 v5, v247, v178
	v_lshlrev_b32_e32 v10, 16, v6
	v_and_b32_e32 v11, 0xffff0000, v6
	v_lshlrev_b32_e32 v12, 16, v7
	v_and_b32_e32 v13, 0xffff0000, v7
	v_lshlrev_b32_e32 v7, 16, v150
	v_lshlrev_b32_e32 v6, 16, v146
	s_waitcnt lgkmcnt(0)
; __device__ __forceinline__ unsigned pk_fp8x4(const f32x4 v) { int r = __builtin_amdgcn_cvt_pk_fp8_f32(v[0], v[1], 0, false); r = __builtin_amdgcn_cvt_pk_fp8_f32(v[2], v[3], r, true); return (unsigned)r; }
; #define GAS __attribute__((address_space(1)))
; #define LAS __attribute__((address_space(3)))
; #define AT_MIX(F, J) do { f8[2 * J] = w1 * bf2f(a0[i].F & 0xffffu) + w2 * bf2f(a1v[i].F & 0xffffu) + bf2f(o.F & 0xffffu); \
;                 f8[2 * J + 1] = w1 * bf2f(a0[i].F >> 16) + w2 * bf2f(a1v[i].F >> 16) + bf2f(o.F >> 16); } while (0)
; __device__ __forceinline__ void attn_unit(const bool FINAL, const bool HN, LAS unsigned char* wl, const bf16_t* qb, const bf16_t* kb, const bf16_t* vb, int tq0, int dil, float sl, bf16x8 (&qr)[8], const bf16_t* nqb, const bf16_t* nkb, const bf16_t* nvb, int ntq0, int ndil, ...
;     ...
;     } else {
; #pragma unroll
;         for (int i = 0; i < 8; ++i) { const int row = 4 * i + rr0, c = cs ^ (row & 15);
;             const float w1 = __shfl(c1, row), w2 = __shfl(c2, row);
;             const v4u o = *(const LAS v4u*)(vbuf + row * 256 + cs * 16);
;             float f8[8];
;     ...
;             AT_MIX(x, 0); AT_MIX(y, 1); AT_MIX(z, 2); AT_MIX(w, 3);
;     ...
;             u32x2 r8; r8.x = pg8::pk_fp8x4((f32x4){f8[0], f8[1], f8[2], f8[3]}); r8.y = pg8::pk_fp8x4((f32x4){f8[4], f8[5], f8[6], f8[7]});
;             *(GAS u32x2*)((GAS unsigned char*)yout + (size_t)(tq0 + dil * row) * 3072 + 8 * c) = r8; }
	v_pk_mul_f32 v[6:7], v[6:7], v[4:5]
	v_lshlrev_b32_e32 v14, 16, v8
	v_add_f32_e32 v6, v6, v7
	v_add_f32_e32 v15, v6, v10
	v_and_b32_e32 v7, 0xffff0000, v150
	v_and_b32_e32 v6, 0xffff0000, v146
	v_pk_mul_f32 v[6:7], v[6:7], v[4:5]
	v_and_b32_e32 v8, 0xffff0000, v8
	v_add_f32_e32 v6, v6, v7
	v_add_f32_e32 v11, v6, v11
	v_lshlrev_b32_e32 v7, 16, v151
	v_lshlrev_b32_e32 v6, 16, v147
	v_pk_mul_f32 v[6:7], v[6:7], v[4:5]
	v_mov_b32_e32 v10, 0
	v_add_f32_e32 v6, v6, v7
	v_add_f32_e32 v12, v6, v12
	v_and_b32_e32 v7, 0xffff0000, v151
	v_and_b32_e32 v6, 0xffff0000, v147
	v_pk_mul_f32 v[6:7], v[6:7], v[4:5]
	v_cvt_pk_fp8_f32 v10, v15, v11
	v_add_f32_e32 v6, v6, v7
	v_add_f32_e32 v13, v6, v13
	v_lshlrev_b32_e32 v7, 16, v152
	v_lshlrev_b32_e32 v6, 16, v148
	v_pk_mul_f32 v[6:7], v[6:7], v[4:5]
	v_mov_b32_e32 v11, 0
	v_add_f32_e32 v6, v6, v7
	v_add_f32_e32 v14, v6, v14
	v_and_b32_e32 v7, 0xffff0000, v152
	v_and_b32_e32 v6, 0xffff0000, v148
	v_pk_mul_f32 v[6:7], v[6:7], v[4:5]
	v_cvt_pk_fp8_f32 v10, v12, v13 op_sel:[0,0,1]
	v_add_f32_e32 v6, v6, v7
	v_add_f32_e32 v8, v6, v8
	v_lshlrev_b32_e32 v7, 16, v153
	v_lshlrev_b32_e32 v6, 16, v149
	v_pk_mul_f32 v[6:7], v[6:7], v[4:5]
	v_cvt_pk_fp8_f32 v11, v14, v8
	v_add_f32_e32 v6, v6, v7
	v_lshlrev_b32_e32 v7, 16, v9
	v_add_f32_e32 v16, v6, v7
	v_and_b32_e32 v7, 0xffff0000, v153
	v_and_b32_e32 v6, 0xffff0000, v149
	v_pk_mul_f32 v[4:5], v[6:7], v[4:5]
	ds_bpermute_b32 v12, v248, v0
	v_add_f32_e32 v4, v4, v5
	v_and_b32_e32 v5, 0xffff0000, v9
	v_add_f32_e32 v4, v4, v5
	v_cvt_pk_fp8_f32 v11, v16, v4 op_sel:[0,0,1]
	v_mad_i64_i32 v[4:5], s[4:5], v194, s97, v[2:3]
	v_lshl_add_u64 v[8:9], v[4:5], 0, v[166:167]
	ds_read_b128 v[4:7], v238 offset:8192
	ds_bpermute_b32 v13, v248, v178
	global_store_dwordx2 v[8:9], v[10:11], off
	ds_read_b128 v[8:11], v239 offset:8192
	s_waitcnt lgkmcnt(2)
	v_lshlrev_b32_e32 v14, 16, v4
	v_and_b32_e32 v15, 0xffff0000, v4
	v_lshlrev_b32_e32 v16, 16, v5
	v_and_b32_e32 v17, 0xffff0000, v5
	v_lshlrev_b32_e32 v5, 16, v142
	v_lshlrev_b32_e32 v4, 16, v138
	s_waitcnt lgkmcnt(1)
	v_pk_mul_f32 v[4:5], v[4:5], v[12:13]
	v_lshlrev_b32_e32 v18, 16, v6
	v_add_f32_e32 v4, v4, v5
	v_add_f32_e32 v14, v4, v14
	v_and_b32_e32 v5, 0xffff0000, v142
	v_and_b32_e32 v4, 0xffff0000, v138
	v_pk_mul_f32 v[4:5], v[4:5], v[12:13]
	v_and_b32_e32 v6, 0xffff0000, v6
	v_add_f32_e32 v4, v4, v5
	v_add_f32_e32 v15, v4, v15
	v_lshlrev_b32_e32 v5, 16, v143
	v_lshlrev_b32_e32 v4, 16, v139
	v_pk_mul_f32 v[4:5], v[4:5], v[12:13]
	s_nop 0
	v_add_f32_e32 v4, v4, v5
	v_add_f32_e32 v16, v4, v16
	v_and_b32_e32 v5, 0xffff0000, v143
	v_and_b32_e32 v4, 0xffff0000, v139
	v_pk_mul_f32 v[4:5], v[4:5], v[12:13]
	s_nop 0
	v_add_f32_e32 v4, v4, v5
	v_add_f32_e32 v17, v4, v17
	v_lshlrev_b32_e32 v5, 16, v144
	v_lshlrev_b32_e32 v4, 16, v140
	v_pk_mul_f32 v[4:5], v[4:5], v[12:13]
	s_nop 0
	v_add_f32_e32 v4, v4, v5
	v_add_f32_e32 v18, v4, v18
	v_and_b32_e32 v5, 0xffff0000, v144
	v_and_b32_e32 v4, 0xffff0000, v140
	v_pk_mul_f32 v[4:5], v[4:5], v[12:13]
	s_nop 0
	v_add_f32_e32 v4, v4, v5
	v_add_f32_e32 v6, v4, v6
	v_lshlrev_b32_e32 v5, 16, v145
	v_lshlrev_b32_e32 v4, 16, v141
	v_pk_mul_f32 v[4:5], v[4:5], v[12:13]
	s_nop 0
	v_add_f32_e32 v4, v4, v5
	v_lshlrev_b32_e32 v5, 16, v7
	v_add_f32_e32 v19, v4, v5
	v_and_b32_e32 v5, 0xffff0000, v145
	v_and_b32_e32 v4, 0xffff0000, v141
	v_pk_mul_f32 v[4:5], v[4:5], v[12:13]
	s_waitcnt lgkmcnt(0)
	v_lshlrev_b32_e32 v13, 16, v9
	v_add_f32_e32 v12, v4, v5
	v_mov_b32_e32 v4, 0
	v_mov_b32_e32 v5, 0
	v_cvt_pk_fp8_f32 v4, v14, v15
	v_cvt_pk_fp8_f32 v5, v18, v6
	v_and_b32_e32 v6, 0xffff0000, v7
	v_add_f32_e32 v6, v12, v6
	v_cvt_pk_fp8_f32 v4, v16, v17 op_sel:[0,0,1]
	v_cvt_pk_fp8_f32 v5, v19, v6 op_sel:[0,0,1]
	v_mad_i64_i32 v[6:7], s[4:5], v192, s97, v[2:3]
	v_lshl_add_u64 v[6:7], v[6:7], 0, v[168:169]
	global_store_dwordx2 v[6:7], v[4:5], off
	ds_bpermute_b32 v4, v249, v0
	ds_bpermute_b32 v5, v249, v178
	v_lshlrev_b32_e32 v7, 16, v134
	v_lshlrev_b32_e32 v6, 16, v130
	v_lshlrev_b32_e32 v12, 16, v8
	v_and_b32_e32 v8, 0xffff0000, v8
	s_waitcnt lgkmcnt(0)
	v_pk_mul_f32 v[6:7], v[6:7], v[4:5]
	v_and_b32_e32 v9, 0xffff0000, v9
	v_add_f32_e32 v6, v6, v7
	v_add_f32_e32 v12, v6, v12
	v_and_b32_e32 v7, 0xffff0000, v134
	v_and_b32_e32 v6, 0xffff0000, v130
	v_pk_mul_f32 v[6:7], v[6:7], v[4:5]
	v_lshlrev_b32_e32 v14, 16, v10
	v_add_f32_e32 v6, v6, v7
	v_add_f32_e32 v15, v6, v8
	v_lshlrev_b32_e32 v7, 16, v135
	v_lshlrev_b32_e32 v6, 16, v131
	v_pk_mul_f32 v[6:7], v[6:7], v[4:5]
	v_and_b32_e32 v10, 0xffff0000, v10
	v_add_f32_e32 v6, v6, v7
	v_add_f32_e32 v13, v6, v13
	v_and_b32_e32 v7, 0xffff0000, v135
	v_and_b32_e32 v6, 0xffff0000, v131
	v_pk_mul_f32 v[6:7], v[6:7], v[4:5]
	v_mov_b32_e32 v8, 0
	v_add_f32_e32 v6, v6, v7
	v_add_f32_e32 v16, v6, v9
	v_lshlrev_b32_e32 v7, 16, v136
	v_lshlrev_b32_e32 v6, 16, v132
	v_pk_mul_f32 v[6:7], v[6:7], v[4:5]
	v_mov_b32_e32 v9, 0
	v_add_f32_e32 v6, v6, v7
	v_add_f32_e32 v14, v6, v14
	v_and_b32_e32 v7, 0xffff0000, v136
	v_and_b32_e32 v6, 0xffff0000, v132
	v_pk_mul_f32 v[6:7], v[6:7], v[4:5]
	v_cvt_pk_fp8_f32 v8, v12, v15
	v_add_f32_e32 v6, v6, v7
	v_add_f32_e32 v10, v6, v10
	v_lshlrev_b32_e32 v7, 16, v137
	v_lshlrev_b32_e32 v6, 16, v133
	v_pk_mul_f32 v[6:7], v[6:7], v[4:5]
	v_cvt_pk_fp8_f32 v9, v14, v10
	v_add_f32_e32 v6, v6, v7
	v_lshlrev_b32_e32 v7, 16, v11
	v_add_f32_e32 v17, v6, v7
	v_and_b32_e32 v7, 0xffff0000, v137
	v_and_b32_e32 v6, 0xffff0000, v133
	v_pk_mul_f32 v[4:5], v[6:7], v[4:5]
	v_cvt_pk_fp8_f32 v8, v13, v16 op_sel:[0,0,1]
	v_add_f32_e32 v4, v4, v5
	v_and_b32_e32 v5, 0xffff0000, v11
	v_add_f32_e32 v4, v4, v5
	v_cvt_pk_fp8_f32 v9, v17, v4 op_sel:[0,0,1]
	v_mad_i64_i32 v[4:5], s[4:5], v190, s97, v[2:3]
	v_lshl_add_u64 v[10:11], v[4:5], 0, v[170:171]
	ds_read_b128 v[4:7], v240 offset:8192
	ds_bpermute_b32 v12, v250, v0
	ds_bpermute_b32 v13, v250, v178
	global_store_dwordx2 v[10:11], v[8:9], off
	ds_read_b128 v[8:11], v241 offset:8192
	s_waitcnt lgkmcnt(3)
; __device__ __forceinline__ unsigned pk_fp8x4(const f32x4 v) { int r = __builtin_amdgcn_cvt_pk_fp8_f32(v[0], v[1], 0, false); r = __builtin_amdgcn_cvt_pk_fp8_f32(v[2], v[3], r, true); return (unsigned)r; }
; #define GAS __attribute__((address_space(1)))
; #define LAS __attribute__((address_space(3)))
; #define AT_MIX(F, J) do { f8[2 * J] = w1 * bf2f(a0[i].F & 0xffffu) + w2 * bf2f(a1v[i].F & 0xffffu) + bf2f(o.F & 0xffffu); \
;                 f8[2 * J + 1] = w1 * bf2f(a0[i].F >> 16) + w2 * bf2f(a1v[i].F >> 16) + bf2f(o.F >> 16); } while (0)
; __device__ __forceinline__ void attn_unit(const bool FINAL, const bool HN, LAS unsigned char* wl, const bf16_t* qb, const bf16_t* kb, const bf16_t* vb, int tq0, int dil, float sl, bf16x8 (&qr)[8], const bf16_t* nqb, const bf16_t* nkb, const bf16_t* nvb, int ntq0, int ndil, ...
;     ...
;     } else {
; #pragma unroll
;         for (int i = 0; i < 8; ++i) { const int row = 4 * i + rr0, c = cs ^ (row & 15);
;             const float w1 = __shfl(c1, row), w2 = __shfl(c2, row);
;             const v4u o = *(const LAS v4u*)(vbuf + row * 256 + cs * 16);
;             float f8[8];
;     ...
;             AT_MIX(x, 0); AT_MIX(y, 1); AT_MIX(z, 2); AT_MIX(w, 3);
;     ...
;             u32x2 r8; r8.x = pg8::pk_fp8x4((f32x4){f8[0], f8[1], f8[2], f8[3]}); r8.y = pg8::pk_fp8x4((f32x4){f8[4], f8[5], f8[6], f8[7]});
;             *(GAS u32x2*)((GAS unsigned char*)yout + (size_t)(tq0 + dil * row) * 3072 + 8 * c) = r8; }
	v_lshlrev_b32_e32 v14, 16, v4
	v_and_b32_e32 v15, 0xffff0000, v4
	v_lshlrev_b32_e32 v16, 16, v5
	v_and_b32_e32 v17, 0xffff0000, v5
	v_lshlrev_b32_e32 v5, 16, v126
	v_lshlrev_b32_e32 v4, 16, v122
	s_waitcnt lgkmcnt(1)
	v_pk_mul_f32 v[4:5], v[4:5], v[12:13]
	v_lshlrev_b32_e32 v18, 16, v6
	v_add_f32_e32 v4, v4, v5
	v_add_f32_e32 v14, v4, v14
	v_and_b32_e32 v5, 0xffff0000, v126
	v_and_b32_e32 v4, 0xffff0000, v122
	v_pk_mul_f32 v[4:5], v[4:5], v[12:13]
	v_and_b32_e32 v6, 0xffff0000, v6
	v_add_f32_e32 v4, v4, v5
	v_add_f32_e32 v15, v4, v15
	v_lshlrev_b32_e32 v5, 16, v127
	v_lshlrev_b32_e32 v4, 16, v123
	v_pk_mul_f32 v[4:5], v[4:5], v[12:13]
	s_nop 0
	v_add_f32_e32 v4, v4, v5
	v_add_f32_e32 v16, v4, v16
	v_and_b32_e32 v5, 0xffff0000, v127
	v_and_b32_e32 v4, 0xffff0000, v123
	v_pk_mul_f32 v[4:5], v[4:5], v[12:13]
	s_nop 0
	v_add_f32_e32 v4, v4, v5
	v_add_f32_e32 v17, v4, v17
	v_lshlrev_b32_e32 v5, 16, v128
	v_lshlrev_b32_e32 v4, 16, v124
	v_pk_mul_f32 v[4:5], v[4:5], v[12:13]
	s_nop 0
	v_add_f32_e32 v4, v4, v5
	v_add_f32_e32 v18, v4, v18
	v_and_b32_e32 v5, 0xffff0000, v128
	v_and_b32_e32 v4, 0xffff0000, v124
	v_pk_mul_f32 v[4:5], v[4:5], v[12:13]
	s_nop 0
	v_add_f32_e32 v4, v4, v5
	v_add_f32_e32 v6, v4, v6
	v_lshlrev_b32_e32 v5, 16, v129
	v_lshlrev_b32_e32 v4, 16, v125
	v_pk_mul_f32 v[4:5], v[4:5], v[12:13]
	s_nop 0
	v_add_f32_e32 v4, v4, v5
	v_lshlrev_b32_e32 v5, 16, v7
	v_add_f32_e32 v19, v4, v5
	v_and_b32_e32 v5, 0xffff0000, v129
	v_and_b32_e32 v4, 0xffff0000, v125
	v_pk_mul_f32 v[4:5], v[4:5], v[12:13]
	s_waitcnt lgkmcnt(0)
	v_lshlrev_b32_e32 v13, 16, v9
	v_add_f32_e32 v12, v4, v5
	v_mov_b32_e32 v4, 0
	v_mov_b32_e32 v5, 0
	v_cvt_pk_fp8_f32 v4, v14, v15
	v_cvt_pk_fp8_f32 v5, v18, v6
	v_and_b32_e32 v6, 0xffff0000, v7
	v_add_f32_e32 v6, v12, v6
	v_cvt_pk_fp8_f32 v4, v16, v17 op_sel:[0,0,1]
	v_cvt_pk_fp8_f32 v5, v19, v6 op_sel:[0,0,1]
	v_mad_i64_i32 v[6:7], s[4:5], v188, s97, v[2:3]
	v_lshl_add_u64 v[6:7], v[6:7], 0, v[164:165]
	global_store_dwordx2 v[6:7], v[4:5], off
	ds_bpermute_b32 v4, v251, v0
	ds_bpermute_b32 v5, v251, v178
	v_lshlrev_b32_e32 v7, 16, v118
	v_lshlrev_b32_e32 v6, 16, v114
	v_lshlrev_b32_e32 v12, 16, v8
	v_and_b32_e32 v8, 0xffff0000, v8
	s_waitcnt lgkmcnt(0)
	v_pk_mul_f32 v[6:7], v[6:7], v[4:5]
	v_and_b32_e32 v9, 0xffff0000, v9
	v_add_f32_e32 v6, v6, v7
	v_add_f32_e32 v12, v6, v12
	v_and_b32_e32 v7, 0xffff0000, v118
	v_and_b32_e32 v6, 0xffff0000, v114
	v_pk_mul_f32 v[6:7], v[6:7], v[4:5]
	v_lshlrev_b32_e32 v14, 16, v10
	v_add_f32_e32 v6, v6, v7
	v_add_f32_e32 v15, v6, v8
	v_lshlrev_b32_e32 v7, 16, v119
	v_lshlrev_b32_e32 v6, 16, v115
	v_pk_mul_f32 v[6:7], v[6:7], v[4:5]
	v_and_b32_e32 v10, 0xffff0000, v10
	v_add_f32_e32 v6, v6, v7
	v_add_f32_e32 v13, v6, v13
	v_and_b32_e32 v7, 0xffff0000, v119
	v_and_b32_e32 v6, 0xffff0000, v115
	v_pk_mul_f32 v[6:7], v[6:7], v[4:5]
	v_mov_b32_e32 v8, 0
	v_add_f32_e32 v6, v6, v7
	v_add_f32_e32 v16, v6, v9
	v_lshlrev_b32_e32 v7, 16, v120
	v_lshlrev_b32_e32 v6, 16, v116
	v_pk_mul_f32 v[6:7], v[6:7], v[4:5]
	v_mov_b32_e32 v9, 0
	v_add_f32_e32 v6, v6, v7
	v_add_f32_e32 v14, v6, v14
	v_and_b32_e32 v7, 0xffff0000, v120
	v_and_b32_e32 v6, 0xffff0000, v116
	v_pk_mul_f32 v[6:7], v[6:7], v[4:5]
	v_cvt_pk_fp8_f32 v8, v12, v15
	v_add_f32_e32 v6, v6, v7
	v_add_f32_e32 v10, v6, v10
	v_lshlrev_b32_e32 v7, 16, v121
	v_lshlrev_b32_e32 v6, 16, v117
	v_pk_mul_f32 v[6:7], v[6:7], v[4:5]
	v_cvt_pk_fp8_f32 v9, v14, v10
	v_add_f32_e32 v6, v6, v7
	v_lshlrev_b32_e32 v7, 16, v11
	v_add_f32_e32 v17, v6, v7
	v_and_b32_e32 v7, 0xffff0000, v121
	v_and_b32_e32 v6, 0xffff0000, v117
	v_pk_mul_f32 v[4:5], v[6:7], v[4:5]
	v_cvt_pk_fp8_f32 v8, v13, v16 op_sel:[0,0,1]
	v_add_f32_e32 v4, v4, v5
	v_and_b32_e32 v5, 0xffff0000, v11
	v_add_f32_e32 v4, v4, v5
	v_cvt_pk_fp8_f32 v9, v17, v4 op_sel:[0,0,1]
	v_mad_i64_i32 v[4:5], s[4:5], v186, s97, v[2:3]
	v_lshl_add_u64 v[10:11], v[4:5], 0, v[172:173]
	ds_read_b128 v[4:7], v242 offset:8192
	ds_bpermute_b32 v12, v252, v0
	ds_bpermute_b32 v13, v252, v178
	global_store_dwordx2 v[10:11], v[8:9], off
	ds_read_b128 v[8:11], v243 offset:8192
	s_waitcnt lgkmcnt(3)
	v_lshlrev_b32_e32 v14, 16, v4
	v_and_b32_e32 v15, 0xffff0000, v4
	v_lshlrev_b32_e32 v16, 16, v5
	v_and_b32_e32 v17, 0xffff0000, v5
	s_waitcnt vmcnt(8)
	v_lshlrev_b32_e32 v5, 16, v78
	v_lshlrev_b32_e32 v4, 16, v74
	s_waitcnt lgkmcnt(1)
; __device__ __forceinline__ unsigned pk_fp8x4(const f32x4 v) { int r = __builtin_amdgcn_cvt_pk_fp8_f32(v[0], v[1], 0, false); r = __builtin_amdgcn_cvt_pk_fp8_f32(v[2], v[3], r, true); return (unsigned)r; }
; #define GAS __attribute__((address_space(1)))
; #define LAS __attribute__((address_space(3)))
; #define SBAR() __builtin_amdgcn_sched_barrier(0)
; __device__ __forceinline__ void at_dma_v(LAS unsigned char* vdst, const bf16_t* vbase, int tq0, int dil, int tile, int lane_) { at_dma_k(vdst, vbase, tq0, dil, tile, lane_); }
; __device__ __forceinline__ void at_dma_k(LAS unsigned char* kdst, const bf16_t* kbase, int tq0, int dil, int tile, int lane_) {
;     int lane = lane_; asm volatile("" : "+v"(lane));
;     const int r0 = lane >> 3; const unsigned c0 = (unsigned)(((lane & 7) ^ r0) << 4);
;     const int t0 = tq0 + dil * (32 * tile + r0 - 64), d8 = 8 * dil;
; #pragma unroll
;     for (int n = 0; n < 4; ++n) { int tkn = t0 + n * d8; tkn = tkn < 0 ? 0 : (tkn > SEQ - 1 ? SEQ - 1 : tkn);
;         const unsigned off = ((unsigned)tkn << 7) + c0;
;         __builtin_amdgcn_global_load_lds((const unsigned*)((const GAS char*)kbase + off), (LAS unsigned*)(kdst + n * 1024), 16, 0, 0); }
; __device__ __forceinline__ void attn_unit(const bool FINAL, const bool HN, LAS unsigned char* wl, const bf16_t* qb, const bf16_t* kb, const bf16_t* vb, int tq0, int dil, float sl, bf16x8 (&qr)[8], const bf16_t* nqb, const bf16_t* nkb, const bf16_t* nvb, int ntq0, int ndil, ...
;     ...
;     } else {
; #pragma unroll
;         for (int i = 0; i < 8; ++i) { const int row = 4 * i + rr0, c = cs ^ (row & 15);
;             const float w1 = __shfl(c1, row), w2 = __shfl(c2, row);
;             const v4u o = *(const LAS v4u*)(vbuf + row * 256 + cs * 16);
;             float f8[8];
;     ...
;             AT_MIX(x, 0); AT_MIX(y, 1); AT_MIX(z, 2); AT_MIX(w, 3);
;     ...
;             u32x2 r8; r8.x = pg8::pk_fp8x4((f32x4){f8[0], f8[1], f8[2], f8[3]}); r8.y = pg8::pk_fp8x4((f32x4){f8[4], f8[5], f8[6], f8[7]});
;             *(GAS u32x2*)((GAS unsigned char*)yout + (size_t)(tq0 + dil * row) * 3072 + 8 * c) = r8; }
;     }
;     asm volatile("s_waitcnt lgkmcnt(0)" ::: "memory"); SBAR();
;     if (HN) at_dma_v(vbuf, nvb, ntq0, ndil, 0, lane);
; }
	v_pk_mul_f32 v[4:5], v[4:5], v[12:13]
	v_lshlrev_b32_e32 v18, 16, v6
	v_add_f32_e32 v4, v4, v5
	v_add_f32_e32 v14, v4, v14
	v_and_b32_e32 v5, 0xffff0000, v78
	v_and_b32_e32 v4, 0xffff0000, v74
	v_pk_mul_f32 v[4:5], v[4:5], v[12:13]
	v_and_b32_e32 v6, 0xffff0000, v6
	v_add_f32_e32 v4, v4, v5
	v_add_f32_e32 v15, v4, v15
	v_lshlrev_b32_e32 v5, 16, v79
	v_lshlrev_b32_e32 v4, 16, v75
	v_pk_mul_f32 v[4:5], v[4:5], v[12:13]
	s_nop 0
	v_add_f32_e32 v4, v4, v5
	v_add_f32_e32 v16, v4, v16
	v_and_b32_e32 v5, 0xffff0000, v79
	v_and_b32_e32 v4, 0xffff0000, v75
	v_pk_mul_f32 v[4:5], v[4:5], v[12:13]
	s_nop 0
	v_add_f32_e32 v4, v4, v5
	v_add_f32_e32 v17, v4, v17
	v_lshlrev_b32_e32 v5, 16, v80
	v_lshlrev_b32_e32 v4, 16, v76
	v_pk_mul_f32 v[4:5], v[4:5], v[12:13]
	s_nop 0
	v_add_f32_e32 v4, v4, v5
	v_add_f32_e32 v18, v4, v18
	v_and_b32_e32 v5, 0xffff0000, v80
	v_and_b32_e32 v4, 0xffff0000, v76
	v_pk_mul_f32 v[4:5], v[4:5], v[12:13]
	s_nop 0
	v_add_f32_e32 v4, v4, v5
	v_add_f32_e32 v6, v4, v6
	v_lshlrev_b32_e32 v5, 16, v81
	v_lshlrev_b32_e32 v4, 16, v77
	v_pk_mul_f32 v[4:5], v[4:5], v[12:13]
	s_nop 0
	v_add_f32_e32 v4, v4, v5
	v_lshlrev_b32_e32 v5, 16, v7
	v_add_f32_e32 v19, v4, v5
	v_and_b32_e32 v5, 0xffff0000, v81
	v_and_b32_e32 v4, 0xffff0000, v77
	v_pk_mul_f32 v[4:5], v[4:5], v[12:13]
	s_waitcnt lgkmcnt(0)
	v_lshlrev_b32_e32 v13, 16, v10
	v_add_f32_e32 v12, v4, v5
	v_mov_b32_e32 v4, 0
	v_mov_b32_e32 v5, 0
	v_cvt_pk_fp8_f32 v4, v14, v15
	v_cvt_pk_fp8_f32 v5, v18, v6
	v_and_b32_e32 v6, 0xffff0000, v7
	v_add_f32_e32 v6, v12, v6
	v_cvt_pk_fp8_f32 v4, v16, v17 op_sel:[0,0,1]
	v_cvt_pk_fp8_f32 v5, v19, v6 op_sel:[0,0,1]
	v_mad_i64_i32 v[6:7], s[4:5], v184, s97, v[2:3]
	v_lshl_add_u64 v[6:7], v[6:7], 0, v[174:175]
	global_store_dwordx2 v[6:7], v[4:5], off
	ds_bpermute_b32 v4, v253, v0
	ds_bpermute_b32 v5, v253, v178
	s_waitcnt vmcnt(7)
	v_lshlrev_b32_e32 v7, 16, v70
	v_lshlrev_b32_e32 v6, 16, v66
	v_lshlrev_b32_e32 v0, 16, v8
	v_and_b32_e32 v8, 0xffff0000, v8
	s_waitcnt lgkmcnt(0)
	v_pk_mul_f32 v[6:7], v[6:7], v[4:5]
	v_lshlrev_b32_e32 v12, 16, v9
	v_add_f32_e32 v6, v6, v7
	v_add_f32_e32 v0, v6, v0
	v_and_b32_e32 v7, 0xffff0000, v70
	v_and_b32_e32 v6, 0xffff0000, v66
	v_pk_mul_f32 v[6:7], v[6:7], v[4:5]
	v_and_b32_e32 v9, 0xffff0000, v9
	v_add_f32_e32 v6, v6, v7
	v_add_f32_e32 v8, v6, v8
	v_lshlrev_b32_e32 v7, 16, v71
	v_lshlrev_b32_e32 v6, 16, v67
	v_pk_mul_f32 v[6:7], v[6:7], v[4:5]
	v_and_b32_e32 v10, 0xffff0000, v10
	v_add_f32_e32 v6, v6, v7
	v_add_f32_e32 v12, v6, v12
	v_and_b32_e32 v7, 0xffff0000, v71
	v_and_b32_e32 v6, 0xffff0000, v67
	v_pk_mul_f32 v[6:7], v[6:7], v[4:5]
	v_mad_i64_i32 v[2:3], s[4:5], v182, s97, v[2:3]
	v_add_f32_e32 v6, v6, v7
	v_add_f32_e32 v9, v6, v9
	v_lshlrev_b32_e32 v7, 16, v72
	v_lshlrev_b32_e32 v6, 16, v68
	v_pk_mul_f32 v[6:7], v[6:7], v[4:5]
	v_lshl_add_u64 v[2:3], v[2:3], 0, v[176:177]
	v_add_f32_e32 v6, v6, v7
	v_add_f32_e32 v13, v6, v13
	v_and_b32_e32 v7, 0xffff0000, v72
	v_and_b32_e32 v6, 0xffff0000, v68
	v_pk_mul_f32 v[6:7], v[6:7], v[4:5]
	s_nop 0
	v_add_f32_e32 v6, v6, v7
	v_add_f32_e32 v10, v6, v10
	v_lshlrev_b32_e32 v7, 16, v73
	v_lshlrev_b32_e32 v6, 16, v69
	v_pk_mul_f32 v[6:7], v[6:7], v[4:5]
	s_nop 0
	v_add_f32_e32 v6, v6, v7
	v_lshlrev_b32_e32 v7, 16, v11
	v_add_f32_e32 v14, v6, v7
	v_and_b32_e32 v7, 0xffff0000, v73
	v_and_b32_e32 v6, 0xffff0000, v69
	v_pk_mul_f32 v[4:5], v[6:7], v[4:5]
	s_nop 0
	v_add_f32_e32 v6, v4, v5
	v_mov_b32_e32 v4, 0
	v_mov_b32_e32 v5, 0
	v_cvt_pk_fp8_f32 v4, v0, v8
	v_cvt_pk_fp8_f32 v5, v13, v10
	v_and_b32_e32 v0, 0xffff0000, v11
	v_add_f32_e32 v0, v6, v0
	v_cvt_pk_fp8_f32 v4, v12, v9 op_sel:[0,0,1]
	v_cvt_pk_fp8_f32 v5, v14, v0 op_sel:[0,0,1]
	global_store_dwordx2 v[2:3], v[4:5], off
	s_waitcnt lgkmcnt(0)
	s_andn2_b64 vcc, exec, s[46:47]
	s_mov_b64 s[4:5], -1
	s_cbranch_vccnz .LBB0_473
	v_mov_b32_e32 v0, v198
	s_sub_i32 s4, s14, 64
	v_ashrrev_i32_e32 v2, 3, v0
	v_bitop3_b32 v0, v0, v2, 7 bitop3:0x6c
	v_add_u32_e32 v3, s4, v2
	v_lshlrev_b32_e32 v0, 4, v0
	v_med3_i32 v3, v3, 0, v244
	s_mov_b32 m0, s39
	v_lshl_add_u32 v3, v3, 7, v0
	s_sub_i32 s4, s14, 56
	global_load_lds_dwordx4 v3, s[30:31]
	v_add_u32_e32 v3, s4, v2
	v_med3_i32 v3, v3, 0, v244
	v_lshl_add_u32 v3, v3, 7, v0
	s_mov_b32 m0, s67
	s_sub_i32 s4, s14, 48
	global_load_lds_dwordx4 v3, s[30:31]
	v_add_u32_e32 v3, s4, v2
	s_sub_i32 s4, s14, 40
	v_med3_i32 v3, v3, 0, v244
	v_add_u32_e32 v2, s4, v2
	v_lshl_add_u32 v3, v3, 7, v0
	s_mov_b32 m0, s82
	v_med3_i32 v2, v2, 0, v244
	global_load_lds_dwordx4 v3, s[30:31]
	v_lshl_add_u32 v0, v2, 7, v0
	s_mov_b32 m0, s66
	s_mov_b64 s[4:5], 0
	global_load_lds_dwordx4 v0, s[30:31]
	s_branch .LBB0_473
